# v57 + in-proj second round: column tiles 8..15 dealt with pn^4 so the transposed-store tiles land on CUs whose first tile has a light epilogue
# speedup vs baseline: 1.0048x; 1.0048x over previous
.LBB0_1264:
	s_and_b64 vcc, exec, s[38:39]
	s_add_i32 s6, s6, 1
	s_cbranch_vccnz .LBB0_1270
	s_lshl_b32 s5, s6, 5
	v_readlane_b32 s40, v255, 8
	s_or_b32 s62, s5, s40
	s_mov_b64 s[42:43], 0
	s_cmpk_lt_u32 s62, 0x5c
	s_mov_b32 s45, s97
	s_mov_b32 s5, s17
	s_mov_b64 s[40:41], 0
	s_cbranch_scc0 .LBB0_1267
	s_lshr_b32 s5, s62, 2
	s_xor_b32 s40, s5, 4
	s_lshr_b32 s41, s5, 3
	s_cmp_eq_u32 s41, 1
	s_cselect_b32 s5, s40, s5
	s_mov_b64 s[40:41], -1
	v_readlane_b32 s45, v255, 10
